# nsa_prep and gdn_post items: all loads issued up front and the rms-norm reductions interleaved (12/8 chains at a time) instead of one serial load-reduce-store chain per head
# speedup vs baseline: 1.2198x; 1.0223x over previous
; DI int TID() { int t = threadIdx.x; asm volatile("" : "+v"(t)); return t; }
; DI unsigned char* WSP(const Params& P) { size_t z = 0; asm volatile("" : "+s"(z)); return P.ws + z; }
; DI float bf2f(u16 h) { return __uint_as_float(((unsigned)h) << 16); }
; DI void gdn_post_item(const Params& P, int l, int it) {
;   const int lane = TID() & 63, w = TID() >> 6;
;   const u16* PROJ = (const u16*)(WSP(P) + WS_PROJ);
;   u16* O = (u16*)(WSP(P) + WS_OM) + (long)2 * T_ * 256;
;   const float wn = P.in[23][l * 64 + lane];
; #pragma unroll 4
;   for (int q = 0; q < 16; ++q) {
;     long t = (long)it * 16 + w * 4 + (q >> 2); int h = q & 3;
;     float o = bf2f(O[t * 256 + h * 64 + lane]);
;     float ss = wave_sum(o * o);
;     float y = o * rsqrtf(ss * (1.f / 64.f) + EPS) * wn;
;     float z = bf2f(PROJ[t * PW + P_GZ + h * 64 + lane]);
.LBB0_180:
	s_or_b64 exec, exec, s[0:1]
	s_waitcnt lgkmcnt(0)
	s_barrier
	ds_read_b32 v0, v165
	s_movk_i32 s0, 0x17ff
	s_waitcnt lgkmcnt(0)
	v_cmp_lt_i32_e32 vcc, s0, v0
	v_readfirstlane_b32 s4, v0
	s_mov_b64 s[0:1], -1
	s_cbranch_vccnz .LBB0_175
	s_cmpk_gt_i32 s4, 0x7ff
	s_cbranch_scc0 .LBB0_193
	s_mov_b32 s28, 0x6dc9c883
	s_mov_b32 s30, 0x54442d18
	s_mov_b32 s34, 0x55555555
	s_mov_b32 s36, 0x11111111
	s_mov_b32 s38, 0x92492492
	s_mov_b32 s40, 0x16c16c17
	s_cmpk_gt_u32 s4, 0xfff
	s_mov_b32 s24, 0x800000
	s_mov_b64 s[26:27], 0x200
	s_mov_b32 s29, 0x3fc45f30
	s_mov_b32 s31, 0xc01921fb
	s_mov_b32 s35, 0xbfb55555
	s_mov_b32 s37, 0xbfa11111
	s_mov_b32 s39, 0xbf924924
	s_mov_b32 s41, 0xbf86c16c
	s_cbranch_scc0 .LBB0_186
	v_mov_b32_e32 v0, v160
	v_readlane_b32 s0, v245, 11
	v_and_b32_e32 v4, 63, v0
	v_readlane_b32 s8, v247, 39
	v_or_b32_e32 v0, s0, v4
	v_ashrrev_i32_e32 v1, 31, v0
	v_readlane_b32 s22, v247, 53
	v_readlane_b32 s23, v247, 54
	v_mov_b32_e32 v2, v160
	s_mov_b64 s[2:3], 0
	s_mov_b64 s[6:7], 0
	v_lshl_add_u64 v[0:1], v[0:1], 2, s[22:23]
	global_load_dword v6, v[0:1], off
	v_ashrrev_i32_e32 v0, 4, v2
	s_lshl_b32 s5, s4, 4
	v_and_b32_e32 v0, -4, v0
	s_add_i32 s46, s5, 0xffff0000
	v_ashrrev_i32_e32 v1, 31, v0
	v_lshl_add_u64 v[2:3], v[0:1], 0, s[46:47]
	v_mbcnt_hi_u32_b32 v0, -1, v184
	v_and_b32_e32 v1, 64, v0
	v_add_u32_e32 v1, 64, v1
	v_xor_b32_e32 v5, 1, v0
	v_cmp_lt_i32_e32 vcc, v5, v1
	v_lshlrev_b32_e32 v162, 1, v4
	s_movk_i32 s5, 0x1600
	v_cndmask_b32_e32 v5, v0, v5, vcc
	v_lshlrev_b32_e32 v7, 2, v5
	v_xor_b32_e32 v5, 2, v0
	v_cmp_lt_i32_e32 vcc, v5, v1
	s_mov_b64 s[0:1], 0
	v_readlane_b32 s9, v247, 40
	v_cndmask_b32_e32 v5, v0, v5, vcc
	v_lshlrev_b32_e32 v8, 2, v5
	v_xor_b32_e32 v5, 4, v0
	v_cmp_lt_i32_e32 vcc, v5, v1
	v_readlane_b32 s10, v247, 41
	v_readlane_b32 s11, v247, 42
	v_cndmask_b32_e32 v5, v0, v5, vcc
	v_lshlrev_b32_e32 v9, 2, v5
	v_xor_b32_e32 v5, 8, v0
	v_cmp_lt_i32_e32 vcc, v5, v1
	v_readlane_b32 s12, v247, 43
	v_readlane_b32 s13, v247, 44
	v_cndmask_b32_e32 v5, v0, v5, vcc
	v_lshlrev_b32_e32 v10, 2, v5
	v_xor_b32_e32 v5, 16, v0
	v_cmp_lt_i32_e32 vcc, v5, v1
	v_readlane_b32 s14, v247, 45
	v_readlane_b32 s15, v247, 46
	v_cndmask_b32_e32 v5, v0, v5, vcc
	v_lshlrev_b32_e32 v11, 2, v5
	v_xor_b32_e32 v5, 32, v0
	v_cmp_lt_i32_e32 vcc, v5, v1
	v_readlane_b32 s16, v247, 47
	v_readlane_b32 s17, v247, 48
	v_cndmask_b32_e32 v0, v0, v5, vcc
	v_mov_b64_e32 v[4:5], s[2:3]
	s_waitcnt vmcnt(5)
	v_lshlrev_b32_e32 v12, 2, v0
	v_lshlrev_b64 v[0:1], 9, v[2:3]
	v_mad_u64_u32 v[4:5], s[2:3], v2, s5, v[4:5]
	v_lshl_add_u64 v[0:1], s[6:7], 0, v[0:1]
	v_readlane_b32 s6, v246, 23
	v_mad_i32_i24 v5, v3, s5, v5
	v_readlane_b32 s2, v246, 25
	v_lshl_add_u64 v[0:1], v[0:1], 0, v[162:163]
	v_readlane_b32 s7, v246, 24
	v_lshl_add_u64 v[2:3], v[4:5], 0, v[162:163]
	v_readlane_b32 s3, v246, 26
	v_lshl_add_u64 v[0:1], s[6:7], 0, v[0:1]
	v_readlane_b32 s18, v247, 49
	v_lshl_add_u64 v[2:3], s[2:3], 0, v[2:3]
	v_readlane_b32 s19, v247, 50
	v_readlane_b32 s20, v247, 51
	v_readlane_b32 s21, v247, 52
	s_movk_i32 s0, 0x1600
	v_lshl_add_u64 v[14:15], v[2:3], 0, s[0:1]
	v_lshl_add_u64 v[16:17], v[14:15], 0, s[0:1]
	v_lshl_add_u64 v[18:19], v[16:17], 0, s[0:1]
	global_load_ushort v20, v[2:3], off offset:-256
	global_load_ushort v36, v[0:1], off offset:-256
	global_load_ushort v21, v[2:3], off offset:-128
	global_load_ushort v37, v[0:1], off offset:-128
	global_load_ushort v22, v[2:3], off
	global_load_ushort v38, v[0:1], off
	global_load_ushort v23, v[2:3], off offset:128
	global_load_ushort v39, v[0:1], off offset:128
	global_load_ushort v24, v[14:15], off offset:-256
	global_load_ushort v40, v[0:1], off offset:256
	global_load_ushort v25, v[14:15], off offset:-128
	global_load_ushort v41, v[0:1], off offset:384
	global_load_ushort v26, v[14:15], off
	global_load_ushort v42, v[0:1], off offset:512
	global_load_ushort v27, v[14:15], off offset:128
	global_load_ushort v43, v[0:1], off offset:640
	global_load_ushort v28, v[16:17], off offset:-256
	global_load_ushort v44, v[0:1], off offset:768
	global_load_ushort v29, v[16:17], off offset:-128
	global_load_ushort v45, v[0:1], off offset:896
	global_load_ushort v30, v[16:17], off
	global_load_ushort v46, v[0:1], off offset:1024
	global_load_ushort v31, v[16:17], off offset:128
	global_load_ushort v47, v[0:1], off offset:1152
	global_load_ushort v32, v[18:19], off offset:-256
	global_load_ushort v48, v[0:1], off offset:1280
	global_load_ushort v33, v[18:19], off offset:-128
	global_load_ushort v49, v[0:1], off offset:1408
	global_load_ushort v34, v[18:19], off
	global_load_ushort v50, v[0:1], off offset:1536
	global_load_ushort v35, v[18:19], off offset:128
	global_load_ushort v51, v[0:1], off offset:1664
	s_waitcnt vmcnt(0)
	v_lshlrev_b32_e32 v36, 16, v36
	v_lshlrev_b32_e32 v37, 16, v37
	v_lshlrev_b32_e32 v38, 16, v38
	v_lshlrev_b32_e32 v39, 16, v39
	v_lshlrev_b32_e32 v40, 16, v40
	v_lshlrev_b32_e32 v41, 16, v41
	v_lshlrev_b32_e32 v42, 16, v42
	v_lshlrev_b32_e32 v43, 16, v43
	v_lshlrev_b32_e32 v20, 16, v20
	v_lshlrev_b32_e32 v21, 16, v21
	v_lshlrev_b32_e32 v22, 16, v22
	v_lshlrev_b32_e32 v23, 16, v23
	v_lshlrev_b32_e32 v24, 16, v24
	v_lshlrev_b32_e32 v25, 16, v25
	v_lshlrev_b32_e32 v26, 16, v26
	v_lshlrev_b32_e32 v27, 16, v27
	v_mul_f32_e32 v52, v36, v36
	v_mul_f32_e32 v53, v37, v37
	v_mul_f32_e32 v54, v38, v38
	v_mul_f32_e32 v55, v39, v39
	v_mul_f32_e32 v56, v40, v40
	v_mul_f32_e32 v57, v41, v41
	v_mul_f32_e32 v58, v42, v42
	v_mul_f32_e32 v59, v43, v43
	ds_bpermute_b32 v60, v7, v52
	ds_bpermute_b32 v61, v7, v53
	ds_bpermute_b32 v62, v7, v54
	ds_bpermute_b32 v63, v7, v55
	ds_bpermute_b32 v64, v7, v56
	ds_bpermute_b32 v65, v7, v57
	ds_bpermute_b32 v66, v7, v58
	ds_bpermute_b32 v67, v7, v59
	v_mul_f32_e32 v68, 0xbfb8aa3b, v20
	v_mul_f32_e32 v69, 0xbfb8aa3b, v21
	v_mul_f32_e32 v70, 0xbfb8aa3b, v22
	v_mul_f32_e32 v71, 0xbfb8aa3b, v23
	v_mul_f32_e32 v72, 0xbfb8aa3b, v24
	v_mul_f32_e32 v73, 0xbfb8aa3b, v25
	v_mul_f32_e32 v74, 0xbfb8aa3b, v26
	v_mul_f32_e32 v75, 0xbfb8aa3b, v27
	v_exp_f32_e32 v68, v68
	v_exp_f32_e32 v69, v69
	v_exp_f32_e32 v70, v70
	v_exp_f32_e32 v71, v71
	v_exp_f32_e32 v72, v72
	v_exp_f32_e32 v73, v73
	v_exp_f32_e32 v74, v74
	v_exp_f32_e32 v75, v75
	s_waitcnt lgkmcnt(0)
; DI float bf2f(u16 h) { return __uint_as_float(((unsigned)h) << 16); }
; DI float siluf_(float x) { return x * sigmoidf_(x); }
; DI void gdn_post_item(const Params& P, int l, int it) {
;     ...
; #pragma unroll 4
;   for (int q = 0; q < 16; ++q) {
;     long t = (long)it * 16 + w * 4 + (q >> 2); int h = q & 3;
;     float o = bf2f(O[t * 256 + h * 64 + lane]);
;     float ss = wave_sum(o * o);
;     float y = o * rsqrtf(ss * (1.f / 64.f) + EPS) * wn;
;     float z = bf2f(PROJ[t * PW + P_GZ + h * 64 + lane]);
;     O[t * 256 + h * 64 + lane] = f2bf(y * siluf_(z));
;   }
	v_fmac_f32_e32 v60, v36, v36
	v_fmac_f32_e32 v61, v37, v37
	v_fmac_f32_e32 v62, v38, v38
	v_fmac_f32_e32 v63, v39, v39
	v_fmac_f32_e32 v64, v40, v40
	v_fmac_f32_e32 v65, v41, v41
	v_fmac_f32_e32 v66, v42, v42
	v_fmac_f32_e32 v67, v43, v43
	ds_bpermute_b32 v52, v8, v60
	ds_bpermute_b32 v53, v8, v61
	ds_bpermute_b32 v54, v8, v62
	ds_bpermute_b32 v55, v8, v63
	ds_bpermute_b32 v56, v8, v64
	ds_bpermute_b32 v57, v8, v65
	ds_bpermute_b32 v58, v8, v66
	ds_bpermute_b32 v59, v8, v67
	v_add_f32_e32 v68, 1.0, v68
	v_add_f32_e32 v69, 1.0, v69
	v_add_f32_e32 v70, 1.0, v70
	v_add_f32_e32 v71, 1.0, v71
	v_add_f32_e32 v72, 1.0, v72
	v_add_f32_e32 v73, 1.0, v73
	v_add_f32_e32 v74, 1.0, v74
	v_add_f32_e32 v75, 1.0, v75
	s_waitcnt lgkmcnt(0)
	v_add_f32_e32 v60, v60, v52
	v_add_f32_e32 v61, v61, v53
	v_add_f32_e32 v62, v62, v54
	v_add_f32_e32 v63, v63, v55
	v_add_f32_e32 v64, v64, v56
	v_add_f32_e32 v65, v65, v57
	v_add_f32_e32 v66, v66, v58
	v_add_f32_e32 v67, v67, v59
	ds_bpermute_b32 v52, v9, v60
	ds_bpermute_b32 v53, v9, v61
	ds_bpermute_b32 v54, v9, v62
	ds_bpermute_b32 v55, v9, v63
	ds_bpermute_b32 v56, v9, v64
	ds_bpermute_b32 v57, v9, v65
	ds_bpermute_b32 v58, v9, v66
	ds_bpermute_b32 v59, v9, v67
	v_rcp_f32_e32 v68, v68
	v_rcp_f32_e32 v69, v69
	v_rcp_f32_e32 v70, v70
	v_rcp_f32_e32 v71, v71
	v_rcp_f32_e32 v72, v72
	v_rcp_f32_e32 v73, v73
	v_rcp_f32_e32 v74, v74
	v_rcp_f32_e32 v75, v75
	s_waitcnt lgkmcnt(0)
	v_add_f32_e32 v60, v60, v52
	v_add_f32_e32 v61, v61, v53
	v_add_f32_e32 v62, v62, v54
	v_add_f32_e32 v63, v63, v55
	v_add_f32_e32 v64, v64, v56
	v_add_f32_e32 v65, v65, v57
	v_add_f32_e32 v66, v66, v58
	v_add_f32_e32 v67, v67, v59
	ds_bpermute_b32 v52, v10, v60
	ds_bpermute_b32 v53, v10, v61
	ds_bpermute_b32 v54, v10, v62
	ds_bpermute_b32 v55, v10, v63
	ds_bpermute_b32 v56, v10, v64
	ds_bpermute_b32 v57, v10, v65
	ds_bpermute_b32 v58, v10, v66
	ds_bpermute_b32 v59, v10, v67
	v_mul_f32_e32 v20, v68, v20
	v_mul_f32_e32 v21, v69, v21
	v_mul_f32_e32 v22, v70, v22
	v_mul_f32_e32 v23, v71, v23
	v_mul_f32_e32 v24, v72, v24
	v_mul_f32_e32 v25, v73, v25
	v_mul_f32_e32 v26, v74, v26
	v_mul_f32_e32 v27, v75, v27
	s_waitcnt lgkmcnt(0)
	v_add_f32_e32 v60, v60, v52
	v_add_f32_e32 v61, v61, v53
	v_add_f32_e32 v62, v62, v54
	v_add_f32_e32 v63, v63, v55
	v_add_f32_e32 v64, v64, v56
	v_add_f32_e32 v65, v65, v57
	v_add_f32_e32 v66, v66, v58
	v_add_f32_e32 v67, v67, v59
	ds_bpermute_b32 v52, v11, v60
	ds_bpermute_b32 v53, v11, v61
	ds_bpermute_b32 v54, v11, v62
	ds_bpermute_b32 v55, v11, v63
	ds_bpermute_b32 v56, v11, v64
	ds_bpermute_b32 v57, v11, v65
	ds_bpermute_b32 v58, v11, v66
	ds_bpermute_b32 v59, v11, v67
	s_waitcnt lgkmcnt(0)
	v_add_f32_e32 v60, v60, v52
	v_add_f32_e32 v61, v61, v53
	v_add_f32_e32 v62, v62, v54
	v_add_f32_e32 v63, v63, v55
	v_add_f32_e32 v64, v64, v56
	v_add_f32_e32 v65, v65, v57
	v_add_f32_e32 v66, v66, v58
	v_add_f32_e32 v67, v67, v59
	ds_bpermute_b32 v52, v12, v60
	ds_bpermute_b32 v53, v12, v61
	ds_bpermute_b32 v54, v12, v62
	ds_bpermute_b32 v55, v12, v63
	ds_bpermute_b32 v56, v12, v64
	ds_bpermute_b32 v57, v12, v65
	ds_bpermute_b32 v58, v12, v66
	ds_bpermute_b32 v59, v12, v67
	s_waitcnt lgkmcnt(0)
	v_add_f32_e32 v60, v60, v52
	v_add_f32_e32 v61, v61, v53
	v_add_f32_e32 v62, v62, v54
	v_add_f32_e32 v63, v63, v55
	v_add_f32_e32 v64, v64, v56
	v_add_f32_e32 v65, v65, v57
	v_add_f32_e32 v66, v66, v58
	v_add_f32_e32 v67, v67, v59
	v_fmamk_f32 v60, v60, 0x3c800000, v164
	v_fmamk_f32 v61, v61, 0x3c800000, v164
	v_fmamk_f32 v62, v62, 0x3c800000, v164
	v_fmamk_f32 v63, v63, 0x3c800000, v164
	v_fmamk_f32 v64, v64, 0x3c800000, v164
	v_fmamk_f32 v65, v65, 0x3c800000, v164
	v_fmamk_f32 v66, v66, 0x3c800000, v164
	v_fmamk_f32 v67, v67, 0x3c800000, v164
	v_rsq_f32_e32 v60, v60
	v_rsq_f32_e32 v61, v61
	v_rsq_f32_e32 v62, v62
	v_rsq_f32_e32 v63, v63
	v_rsq_f32_e32 v64, v64
	v_rsq_f32_e32 v65, v65
	v_rsq_f32_e32 v66, v66
	v_rsq_f32_e32 v67, v67
	v_mul_f32_e32 v36, v60, v36
	v_mul_f32_e32 v37, v61, v37
	v_mul_f32_e32 v38, v62, v38
	v_mul_f32_e32 v39, v63, v39
	v_mul_f32_e32 v40, v64, v40
	v_mul_f32_e32 v41, v65, v41
	v_mul_f32_e32 v42, v66, v42
	v_mul_f32_e32 v43, v67, v43
	v_mul_f32_e32 v36, v6, v36
	v_mul_f32_e32 v37, v6, v37
	v_mul_f32_e32 v38, v6, v38
	v_mul_f32_e32 v39, v6, v39
	v_mul_f32_e32 v40, v6, v40
	v_mul_f32_e32 v41, v6, v41
	v_mul_f32_e32 v42, v6, v42
	v_mul_f32_e32 v43, v6, v43
	v_mul_f32_e32 v36, v20, v36
	v_mul_f32_e32 v37, v21, v37
	v_mul_f32_e32 v38, v22, v38
	v_mul_f32_e32 v39, v23, v39
	v_mul_f32_e32 v40, v24, v40
	v_mul_f32_e32 v41, v25, v41
	v_mul_f32_e32 v42, v26, v42
	v_mul_f32_e32 v43, v27, v43
	v_cvt_pk_bf16_f32 v36, v36, v36
	v_cvt_pk_bf16_f32 v37, v37, v37
	v_cvt_pk_bf16_f32 v38, v38, v38
	v_cvt_pk_bf16_f32 v39, v39, v39
	v_cvt_pk_bf16_f32 v40, v40, v40
	v_cvt_pk_bf16_f32 v41, v41, v41
	v_cvt_pk_bf16_f32 v42, v42, v42
	v_cvt_pk_bf16_f32 v43, v43, v43
	global_store_short v[0:1], v36, off offset:-256
	global_store_short v[0:1], v37, off offset:-128
	global_store_short v[0:1], v38, off
	global_store_short v[0:1], v39, off offset:128
	global_store_short v[0:1], v40, off offset:256
	global_store_short v[0:1], v41, off offset:384
	global_store_short v[0:1], v42, off offset:512
	global_store_short v[0:1], v43, off offset:640
	v_lshlrev_b32_e32 v44, 16, v44
	v_lshlrev_b32_e32 v45, 16, v45
	v_lshlrev_b32_e32 v46, 16, v46
	v_lshlrev_b32_e32 v47, 16, v47
	v_lshlrev_b32_e32 v48, 16, v48
	v_lshlrev_b32_e32 v49, 16, v49
	v_lshlrev_b32_e32 v50, 16, v50
	v_lshlrev_b32_e32 v51, 16, v51
	v_lshlrev_b32_e32 v28, 16, v28
	v_lshlrev_b32_e32 v29, 16, v29
	v_lshlrev_b32_e32 v30, 16, v30
	v_lshlrev_b32_e32 v31, 16, v31
	v_lshlrev_b32_e32 v32, 16, v32
	v_lshlrev_b32_e32 v33, 16, v33
	v_lshlrev_b32_e32 v34, 16, v34
	v_lshlrev_b32_e32 v35, 16, v35
	v_mul_f32_e32 v52, v44, v44
	v_mul_f32_e32 v53, v45, v45
	v_mul_f32_e32 v54, v46, v46
	v_mul_f32_e32 v55, v47, v47
	v_mul_f32_e32 v56, v48, v48
	v_mul_f32_e32 v57, v49, v49
	v_mul_f32_e32 v58, v50, v50
	v_mul_f32_e32 v59, v51, v51
	ds_bpermute_b32 v60, v7, v52
	ds_bpermute_b32 v61, v7, v53
	ds_bpermute_b32 v62, v7, v54
	ds_bpermute_b32 v63, v7, v55
	ds_bpermute_b32 v64, v7, v56
	ds_bpermute_b32 v65, v7, v57
	ds_bpermute_b32 v66, v7, v58
	ds_bpermute_b32 v67, v7, v59
	v_mul_f32_e32 v68, 0xbfb8aa3b, v28
	v_mul_f32_e32 v69, 0xbfb8aa3b, v29
	v_mul_f32_e32 v70, 0xbfb8aa3b, v30
	v_mul_f32_e32 v71, 0xbfb8aa3b, v31
	v_mul_f32_e32 v72, 0xbfb8aa3b, v32
	v_mul_f32_e32 v73, 0xbfb8aa3b, v33
	v_mul_f32_e32 v74, 0xbfb8aa3b, v34
	v_mul_f32_e32 v75, 0xbfb8aa3b, v35
	v_exp_f32_e32 v68, v68
	v_exp_f32_e32 v69, v69
	v_exp_f32_e32 v70, v70
	v_exp_f32_e32 v71, v71
	v_exp_f32_e32 v72, v72
	v_exp_f32_e32 v73, v73
	v_exp_f32_e32 v74, v74
	v_exp_f32_e32 v75, v75
	s_waitcnt lgkmcnt(0)
; DI float bf2f(u16 h) { return __uint_as_float(((unsigned)h) << 16); }
; DI float siluf_(float x) { return x * sigmoidf_(x); }
; DI void gdn_post_item(const Params& P, int l, int it) {
;     ...
; #pragma unroll 4
;   for (int q = 0; q < 16; ++q) {
;     long t = (long)it * 16 + w * 4 + (q >> 2); int h = q & 3;
;     float o = bf2f(O[t * 256 + h * 64 + lane]);
;     float ss = wave_sum(o * o);
;     float y = o * rsqrtf(ss * (1.f / 64.f) + EPS) * wn;
;     float z = bf2f(PROJ[t * PW + P_GZ + h * 64 + lane]);
;     O[t * 256 + h * 64 + lane] = f2bf(y * siluf_(z));
;   }
	v_fmac_f32_e32 v60, v44, v44
	v_fmac_f32_e32 v61, v45, v45
	v_fmac_f32_e32 v62, v46, v46
	v_fmac_f32_e32 v63, v47, v47
	v_fmac_f32_e32 v64, v48, v48
	v_fmac_f32_e32 v65, v49, v49
	v_fmac_f32_e32 v66, v50, v50
	v_fmac_f32_e32 v67, v51, v51
	ds_bpermute_b32 v52, v8, v60
	ds_bpermute_b32 v53, v8, v61
	ds_bpermute_b32 v54, v8, v62
	ds_bpermute_b32 v55, v8, v63
	ds_bpermute_b32 v56, v8, v64
	ds_bpermute_b32 v57, v8, v65
	ds_bpermute_b32 v58, v8, v66
	ds_bpermute_b32 v59, v8, v67
	v_add_f32_e32 v68, 1.0, v68
	v_add_f32_e32 v69, 1.0, v69
	v_add_f32_e32 v70, 1.0, v70
	v_add_f32_e32 v71, 1.0, v71
	v_add_f32_e32 v72, 1.0, v72
	v_add_f32_e32 v73, 1.0, v73
	v_add_f32_e32 v74, 1.0, v74
	v_add_f32_e32 v75, 1.0, v75
	s_waitcnt lgkmcnt(0)
	v_add_f32_e32 v60, v60, v52
	v_add_f32_e32 v61, v61, v53
	v_add_f32_e32 v62, v62, v54
	v_add_f32_e32 v63, v63, v55
	v_add_f32_e32 v64, v64, v56
	v_add_f32_e32 v65, v65, v57
	v_add_f32_e32 v66, v66, v58
	v_add_f32_e32 v67, v67, v59
	ds_bpermute_b32 v52, v9, v60
	ds_bpermute_b32 v53, v9, v61
	ds_bpermute_b32 v54, v9, v62
	ds_bpermute_b32 v55, v9, v63
	ds_bpermute_b32 v56, v9, v64
	ds_bpermute_b32 v57, v9, v65
	ds_bpermute_b32 v58, v9, v66
	ds_bpermute_b32 v59, v9, v67
	v_rcp_f32_e32 v68, v68
	v_rcp_f32_e32 v69, v69
	v_rcp_f32_e32 v70, v70
	v_rcp_f32_e32 v71, v71
	v_rcp_f32_e32 v72, v72
	v_rcp_f32_e32 v73, v73
	v_rcp_f32_e32 v74, v74
	v_rcp_f32_e32 v75, v75
	s_waitcnt lgkmcnt(0)
	v_add_f32_e32 v60, v60, v52
	v_add_f32_e32 v61, v61, v53
	v_add_f32_e32 v62, v62, v54
	v_add_f32_e32 v63, v63, v55
	v_add_f32_e32 v64, v64, v56
	v_add_f32_e32 v65, v65, v57
	v_add_f32_e32 v66, v66, v58
	v_add_f32_e32 v67, v67, v59
	ds_bpermute_b32 v52, v10, v60
	ds_bpermute_b32 v53, v10, v61
	ds_bpermute_b32 v54, v10, v62
	ds_bpermute_b32 v55, v10, v63
	ds_bpermute_b32 v56, v10, v64
	ds_bpermute_b32 v57, v10, v65
	ds_bpermute_b32 v58, v10, v66
	ds_bpermute_b32 v59, v10, v67
	v_mul_f32_e32 v28, v68, v28
	v_mul_f32_e32 v29, v69, v29
	v_mul_f32_e32 v30, v70, v30
	v_mul_f32_e32 v31, v71, v31
	v_mul_f32_e32 v32, v72, v32
	v_mul_f32_e32 v33, v73, v33
	v_mul_f32_e32 v34, v74, v34
	v_mul_f32_e32 v35, v75, v35
	s_waitcnt lgkmcnt(0)
	v_add_f32_e32 v60, v60, v52
	v_add_f32_e32 v61, v61, v53
	v_add_f32_e32 v62, v62, v54
	v_add_f32_e32 v63, v63, v55
	v_add_f32_e32 v64, v64, v56
	v_add_f32_e32 v65, v65, v57
	v_add_f32_e32 v66, v66, v58
	v_add_f32_e32 v67, v67, v59
	ds_bpermute_b32 v52, v11, v60
	ds_bpermute_b32 v53, v11, v61
	ds_bpermute_b32 v54, v11, v62
	ds_bpermute_b32 v55, v11, v63
	ds_bpermute_b32 v56, v11, v64
	ds_bpermute_b32 v57, v11, v65
	ds_bpermute_b32 v58, v11, v66
	ds_bpermute_b32 v59, v11, v67
	s_waitcnt lgkmcnt(0)
	v_add_f32_e32 v60, v60, v52
	v_add_f32_e32 v61, v61, v53
	v_add_f32_e32 v62, v62, v54
	v_add_f32_e32 v63, v63, v55
	v_add_f32_e32 v64, v64, v56
	v_add_f32_e32 v65, v65, v57
	v_add_f32_e32 v66, v66, v58
	v_add_f32_e32 v67, v67, v59
	ds_bpermute_b32 v52, v12, v60
	ds_bpermute_b32 v53, v12, v61
	ds_bpermute_b32 v54, v12, v62
	ds_bpermute_b32 v55, v12, v63
	ds_bpermute_b32 v56, v12, v64
	ds_bpermute_b32 v57, v12, v65
	ds_bpermute_b32 v58, v12, v66
	ds_bpermute_b32 v59, v12, v67
	s_waitcnt lgkmcnt(0)
	v_add_f32_e32 v60, v60, v52
	v_add_f32_e32 v61, v61, v53
	v_add_f32_e32 v62, v62, v54
	v_add_f32_e32 v63, v63, v55
	v_add_f32_e32 v64, v64, v56
	v_add_f32_e32 v65, v65, v57
	v_add_f32_e32 v66, v66, v58
	v_add_f32_e32 v67, v67, v59
	v_fmamk_f32 v60, v60, 0x3c800000, v164
	v_fmamk_f32 v61, v61, 0x3c800000, v164
	v_fmamk_f32 v62, v62, 0x3c800000, v164
	v_fmamk_f32 v63, v63, 0x3c800000, v164
	v_fmamk_f32 v64, v64, 0x3c800000, v164
	v_fmamk_f32 v65, v65, 0x3c800000, v164
	v_fmamk_f32 v66, v66, 0x3c800000, v164
	v_fmamk_f32 v67, v67, 0x3c800000, v164
	v_rsq_f32_e32 v60, v60
	v_rsq_f32_e32 v61, v61
	v_rsq_f32_e32 v62, v62
	v_rsq_f32_e32 v63, v63
	v_rsq_f32_e32 v64, v64
	v_rsq_f32_e32 v65, v65
	v_rsq_f32_e32 v66, v66
	v_rsq_f32_e32 v67, v67
	v_mul_f32_e32 v44, v60, v44
	v_mul_f32_e32 v45, v61, v45
	v_mul_f32_e32 v46, v62, v46
	v_mul_f32_e32 v47, v63, v47
	v_mul_f32_e32 v48, v64, v48
	v_mul_f32_e32 v49, v65, v49
	v_mul_f32_e32 v50, v66, v50
	v_mul_f32_e32 v51, v67, v51
	v_mul_f32_e32 v44, v6, v44
	v_mul_f32_e32 v45, v6, v45
	v_mul_f32_e32 v46, v6, v46
	v_mul_f32_e32 v47, v6, v47
	v_mul_f32_e32 v48, v6, v48
	v_mul_f32_e32 v49, v6, v49
	v_mul_f32_e32 v50, v6, v50
	v_mul_f32_e32 v51, v6, v51
	v_mul_f32_e32 v44, v28, v44
	v_mul_f32_e32 v45, v29, v45
	v_mul_f32_e32 v46, v30, v46
	v_mul_f32_e32 v47, v31, v47
	v_mul_f32_e32 v48, v32, v48
	v_mul_f32_e32 v49, v33, v49
	v_mul_f32_e32 v50, v34, v50
	v_mul_f32_e32 v51, v35, v51
	v_cvt_pk_bf16_f32 v44, v44, v44
	v_cvt_pk_bf16_f32 v45, v45, v45
	v_cvt_pk_bf16_f32 v46, v46, v46
	v_cvt_pk_bf16_f32 v47, v47, v47
	v_cvt_pk_bf16_f32 v48, v48, v48
	v_cvt_pk_bf16_f32 v49, v49, v49
	v_cvt_pk_bf16_f32 v50, v50, v50
	v_cvt_pk_bf16_f32 v51, v51, v51
	global_store_short v[0:1], v44, off offset:768
	global_store_short v[0:1], v45, off offset:896
	global_store_short v[0:1], v46, off offset:1024
	global_store_short v[0:1], v47, off offset:1152
	global_store_short v[0:1], v48, off offset:1280
	global_store_short v[0:1], v49, off offset:1408
	global_store_short v[0:1], v50, off offset:1536
	global_store_short v[0:1], v51, off offset:1664
	s_mov_b64 s[0:1], 0

; DI int TID() { int t = threadIdx.x; asm volatile("" : "+v"(t)); return t; }
; DI unsigned char* WSP(const Params& P) { size_t z = 0; asm volatile("" : "+s"(z)); return P.ws + z; }
; DI float bf2f(u16 h) { return __uint_as_float(((unsigned)h) << 16); }
; DI void nsa_prep_item(const Params& P, int l, int it) {
;   const int lane = TID() & 63, w = TID() >> 6;
;   u16* PROJ = (u16*)(WSP(P) + WS_PROJ);
;   u16* QR = (u16*)(WSP(P) + WS_QR);
;   const float* COS = (const float*)(WSP(P) + WS_COS);
;   const float* SIN = (const float*)(WSP(P) + WS_SIN);
;   for (int tt = 0; tt < 4; ++tt) {
;     const long t = (long)it * 16 + w * 4 + tt;
;     const float cs = COS[t * 8 + (lane & 7)], sn = SIN[t * 8 + (lane & 7)];
; #pragma unroll
;     for (int g = 0; g < 6; ++g) {
;       const int col = (g < 4) ? (P_Q + g * 64) : (g == 4 ? P_KV + 128 : P_KV + 256);
;       const float wg = (g < 4) ? P.in[4][l * 64 + lane] : P.in[5][(l * 3 + (g - 3)) * 64 + lane];
;       u16* ptr = PROJ + t * PW + col + lane;
;       float v = bf2f(*ptr);
.LBB0_507:
	s_or_b64 exec, exec, s[0:1]
	s_waitcnt lgkmcnt(0)
	s_barrier
	ds_read_b32 v0, v165
	s_movk_i32 s0, 0x183f
	s_waitcnt lgkmcnt(0)
	v_cmp_lt_i32_e32 vcc, s0, v0
	v_readfirstlane_b32 s16, v0
	s_mov_b64 s[0:1], -1
	s_cbranch_vccnz .LBB0_502
	s_cmp_gt_i32 s16, 63
	s_cbranch_scc0 .LBB0_614
	s_cmpk_gt_u32 s16, 0x83f
	s_cbranch_scc0 .LBB0_519
	s_cmpk_gt_u32 s16, 0x103f
	s_cbranch_scc0 .LBB0_514
	v_mov_b32_e32 v11, v160
	v_readlane_b32 s0, v245, 11
	s_waitcnt vmcnt(6)
	v_and_b32_e32 v17, 63, v11
	v_readlane_b32 s72, v247, 7
	v_or_b32_e32 v0, s0, v17
	v_ashrrev_i32_e32 v1, 31, v0
	v_or_b32_e32 v2, s14, v17
	v_readlane_b32 s80, v247, 15
	v_readlane_b32 s81, v247, 16
	v_mov_b32_e32 v6, v160
	s_mov_b64 s[4:5], 0
	s_mov_b64 s[6:7], 0
	s_mov_b64 s[10:11], 0
	s_mov_b64 s[12:13], 0
	v_ashrrev_i32_e32 v3, 31, v2
	v_or_b32_e32 v4, s15, v17
	v_readlane_b32 s82, v247, 17
	v_readlane_b32 s83, v247, 18
	v_lshl_add_u64 v[0:1], v[0:1], 2, s[80:81]
	v_ashrrev_i32_e32 v5, 31, v4
	global_load_dword v8, v[0:1], off
	v_lshl_add_u64 v[0:1], v[2:3], 2, s[82:83]
	v_lshl_add_u64 v[2:3], v[4:5], 2, s[82:83]
	global_load_dword v9, v[0:1], off
	global_load_dword v10, v[2:3], off
	v_ashrrev_i32_e32 v0, 4, v6
	s_lshl_b32 s0, s16, 4
	v_and_b32_e32 v0, -4, v0
	s_add_i32 s46, s0, 0xfffefc00
	v_ashrrev_i32_e32 v1, 31, v0
	v_lshl_add_u64 v[6:7], v[0:1], 0, s[46:47]
	v_and_b32_e32 v0, 64, v185
	v_add_u32_e32 v0, 64, v0
	v_xor_b32_e32 v1, 1, v185
	v_cmp_lt_i32_e32 vcc, v1, v0
	v_and_b32_e32 v4, 7, v11
	v_lshlrev_b64 v[2:3], 5, v[6:7]
	v_cndmask_b32_e32 v1, v185, v1, vcc
	v_lshlrev_b32_e32 v11, 2, v1
	v_xor_b32_e32 v1, 2, v185
	v_cmp_lt_i32_e32 vcc, v1, v0
	v_lshlrev_b32_e32 v162, 2, v4
	v_lshlrev_b64 v[4:5], 9, v[6:7]
	v_cndmask_b32_e32 v1, v185, v1, vcc
	s_waitcnt vmcnt(7)
	v_lshlrev_b32_e32 v12, 2, v1
	v_xor_b32_e32 v1, 4, v185
	v_cmp_lt_i32_e32 vcc, v1, v0
	v_lshl_add_u64 v[4:5], s[6:7], 0, v[4:5]
	v_readlane_b32 s6, v246, 33
	v_cndmask_b32_e32 v1, v185, v1, vcc
	v_lshlrev_b32_e32 v13, 2, v1
	v_xor_b32_e32 v1, 8, v185
	v_cmp_lt_i32_e32 vcc, v1, v0
	v_readlane_b32 s7, v246, 34
	v_mov_b64_e32 v[18:19], s[4:5]
	v_cndmask_b32_e32 v1, v185, v1, vcc
	v_lshlrev_b32_e32 v14, 2, v1
	v_xor_b32_e32 v1, 16, v185
	v_cmp_lt_i32_e32 vcc, v1, v0
	s_mov_b64 s[8:9], 0
	v_cmp_gt_u32_e64 s[0:1], 16, v17
	v_cndmask_b32_e32 v1, v185, v1, vcc
	v_lshlrev_b32_e32 v15, 2, v1
	v_xor_b32_e32 v1, 32, v185
	v_cmp_lt_i32_e32 vcc, v1, v0
	s_mov_b64 s[18:19], 0x200
	v_readlane_b32 s73, v247, 8
	v_cndmask_b32_e32 v0, v185, v1, vcc
	v_lshlrev_b32_e32 v16, 2, v0
	v_lshl_add_u64 v[0:1], s[12:13], 0, v[2:3]
	v_lshl_add_u64 v[2:3], s[10:11], 0, v[2:3]
	v_lshl_add_u64 v[0:1], v[0:1], 0, v[162:163]
	v_lshl_add_u64 v[2:3], v[2:3], 0, v[162:163]
	v_lshlrev_b32_e32 v162, 1, v17
	v_lshl_add_u64 v[4:5], v[4:5], 0, v[162:163]
	v_lshl_add_u64 v[4:5], s[6:7], 0, v[4:5]
	s_movk_i32 s6, 0x1600
	v_mad_u64_u32 v[18:19], s[4:5], v6, s6, v[18:19]
	v_readlane_b32 s12, v246, 29
	v_readlane_b32 s10, v246, 31
	v_mad_i32_i24 v19, v7, s6, v19
	v_readlane_b32 s4, v246, 35
	v_readlane_b32 s13, v246, 30
	v_readlane_b32 s11, v246, 32
	v_lshl_add_u64 v[6:7], v[18:19], 0, v[162:163]
	v_readlane_b32 s5, v246, 36
	v_cmp_gt_u32_e32 vcc, 8, v17
	v_lshl_add_u64 v[0:1], s[12:13], 0, v[0:1]
	v_lshl_add_u64 v[2:3], s[10:11], 0, v[2:3]
	v_lshl_add_u64 v[6:7], s[4:5], 0, v[6:7]
	s_mov_b32 s10, 0x800000
	s_mov_b64 s[12:13], 0x1600
	v_readlane_b32 s74, v247, 9
	v_readlane_b32 s75, v247, 10
	v_readlane_b32 s76, v247, 11
	v_readlane_b32 s77, v247, 12
	v_readlane_b32 s78, v247, 13
	v_readlane_b32 s79, v247, 14
	v_readlane_b32 s84, v247, 19
	v_readlane_b32 s85, v247, 20
	v_readlane_b32 s86, v247, 21
	v_readlane_b32 s87, v247, 22
	v_lshl_add_u64 v[26:27], v[6:7], 0, s[12:13]
	v_lshl_add_u64 v[28:29], v[26:27], 0, s[12:13]
	v_lshl_add_u64 v[30:31], v[28:29], 0, s[12:13]
	global_load_ushort v40, v[6:7], off offset:-768
	global_load_ushort v41, v[6:7], off offset:-640
	global_load_ushort v42, v[6:7], off offset:-512
	global_load_ushort v43, v[6:7], off offset:-384
	global_load_ushort v44, v[6:7], off
	global_load_ushort v45, v[6:7], off offset:256
	global_load_dword v32, v[2:3], off
	global_load_dword v36, v[0:1], off
	global_load_ushort v46, v[26:27], off offset:-768
	global_load_ushort v47, v[26:27], off offset:-640
	global_load_ushort v48, v[26:27], off offset:-512
	global_load_ushort v49, v[26:27], off offset:-384
	global_load_ushort v50, v[26:27], off
	global_load_ushort v51, v[26:27], off offset:256
	global_load_dword v33, v[2:3], off offset:32
	global_load_dword v37, v[0:1], off offset:32
	global_load_ushort v52, v[28:29], off offset:-768
	global_load_ushort v53, v[28:29], off offset:-640
	global_load_ushort v54, v[28:29], off offset:-512
	global_load_ushort v55, v[28:29], off offset:-384
	global_load_ushort v56, v[28:29], off
	global_load_ushort v57, v[28:29], off offset:256
	global_load_dword v34, v[2:3], off offset:64
	global_load_dword v38, v[0:1], off offset:64
	global_load_ushort v58, v[30:31], off offset:-768
	global_load_ushort v59, v[30:31], off offset:-640
	global_load_ushort v60, v[30:31], off offset:-512
	global_load_ushort v61, v[30:31], off offset:-384
	global_load_ushort v62, v[30:31], off
	global_load_ushort v63, v[30:31], off offset:256
	global_load_dword v35, v[2:3], off offset:96
	global_load_dword v39, v[0:1], off offset:96
	s_waitcnt vmcnt(0)
; DI float bf2f(u16 h) { return __uint_as_float(((unsigned)h) << 16); }
; DI void nsa_prep_item(const Params& P, int l, int it) {
;     ...
;   for (int tt = 0; tt < 4; ++tt) {
;     const long t = (long)it * 16 + w * 4 + tt;
;     const float cs = COS[t * 8 + (lane & 7)], sn = SIN[t * 8 + (lane & 7)];
; #pragma unroll
;     for (int g = 0; g < 6; ++g) {
;       const int col = (g < 4) ? (P_Q + g * 64) : (g == 4 ? P_KV + 128 : P_KV + 256);
;       const float wg = (g < 4) ? P.in[4][l * 64 + lane] : P.in[5][(l * 3 + (g - 3)) * 64 + lane];
;       u16* ptr = PROJ + t * PW + col + lane;
;       float v = bf2f(*ptr);
;       float ss = wave_sum(v * v);
;       float y = v * rsqrtf(ss * (1.f / 64.f) + EPS) * wg;
	v_lshlrev_b32_e32 v40, 16, v40
	v_lshlrev_b32_e32 v41, 16, v41
	v_lshlrev_b32_e32 v42, 16, v42
	v_lshlrev_b32_e32 v43, 16, v43
	v_lshlrev_b32_e32 v44, 16, v44
	v_lshlrev_b32_e32 v45, 16, v45
	v_lshlrev_b32_e32 v46, 16, v46
	v_lshlrev_b32_e32 v47, 16, v47
	v_lshlrev_b32_e32 v48, 16, v48
	v_lshlrev_b32_e32 v49, 16, v49
	v_lshlrev_b32_e32 v50, 16, v50
	v_lshlrev_b32_e32 v51, 16, v51
	v_mul_f32_e32 v64, v40, v40
	v_mul_f32_e32 v65, v41, v41
	v_mul_f32_e32 v66, v42, v42
	v_mul_f32_e32 v67, v43, v43
	v_mul_f32_e32 v68, v44, v44
	v_mul_f32_e32 v69, v45, v45
	v_mul_f32_e32 v70, v46, v46
	v_mul_f32_e32 v71, v47, v47
	v_mul_f32_e32 v72, v48, v48
	v_mul_f32_e32 v73, v49, v49
	v_mul_f32_e32 v74, v50, v50
	v_mul_f32_e32 v75, v51, v51
	ds_bpermute_b32 v76, v11, v64
	ds_bpermute_b32 v77, v11, v65
	ds_bpermute_b32 v78, v11, v66
	ds_bpermute_b32 v79, v11, v67
	ds_bpermute_b32 v80, v11, v68
	ds_bpermute_b32 v81, v11, v69
	ds_bpermute_b32 v82, v11, v70
	ds_bpermute_b32 v83, v11, v71
	ds_bpermute_b32 v84, v11, v72
	ds_bpermute_b32 v85, v11, v73
	ds_bpermute_b32 v86, v11, v74
	ds_bpermute_b32 v87, v11, v75
	s_waitcnt lgkmcnt(0)
	v_fmac_f32_e32 v76, v40, v40
	v_fmac_f32_e32 v77, v41, v41
	v_fmac_f32_e32 v78, v42, v42
	v_fmac_f32_e32 v79, v43, v43
	v_fmac_f32_e32 v80, v44, v44
	v_fmac_f32_e32 v81, v45, v45
	v_fmac_f32_e32 v82, v46, v46
	v_fmac_f32_e32 v83, v47, v47
	v_fmac_f32_e32 v84, v48, v48
	v_fmac_f32_e32 v85, v49, v49
	v_fmac_f32_e32 v86, v50, v50
	v_fmac_f32_e32 v87, v51, v51
	ds_bpermute_b32 v64, v12, v76
	ds_bpermute_b32 v65, v12, v77
	ds_bpermute_b32 v66, v12, v78
	ds_bpermute_b32 v67, v12, v79
	ds_bpermute_b32 v68, v12, v80
	ds_bpermute_b32 v69, v12, v81
	ds_bpermute_b32 v70, v12, v82
	ds_bpermute_b32 v71, v12, v83
	ds_bpermute_b32 v72, v12, v84
	ds_bpermute_b32 v73, v12, v85
	ds_bpermute_b32 v74, v12, v86
	ds_bpermute_b32 v75, v12, v87
	s_waitcnt lgkmcnt(0)
	v_add_f32_e32 v76, v76, v64
	v_add_f32_e32 v77, v77, v65
	v_add_f32_e32 v78, v78, v66
	v_add_f32_e32 v79, v79, v67
	v_add_f32_e32 v80, v80, v68
	v_add_f32_e32 v81, v81, v69
	v_add_f32_e32 v82, v82, v70
	v_add_f32_e32 v83, v83, v71
	v_add_f32_e32 v84, v84, v72
	v_add_f32_e32 v85, v85, v73
	v_add_f32_e32 v86, v86, v74
	v_add_f32_e32 v87, v87, v75
	ds_bpermute_b32 v64, v13, v76
	ds_bpermute_b32 v65, v13, v77
	ds_bpermute_b32 v66, v13, v78
	ds_bpermute_b32 v67, v13, v79
	ds_bpermute_b32 v68, v13, v80
	ds_bpermute_b32 v69, v13, v81
	ds_bpermute_b32 v70, v13, v82
	ds_bpermute_b32 v71, v13, v83
	ds_bpermute_b32 v72, v13, v84
	ds_bpermute_b32 v73, v13, v85
	ds_bpermute_b32 v74, v13, v86
	ds_bpermute_b32 v75, v13, v87
	s_waitcnt lgkmcnt(0)
	v_add_f32_e32 v76, v76, v64
	v_add_f32_e32 v77, v77, v65
	v_add_f32_e32 v78, v78, v66
	v_add_f32_e32 v79, v79, v67
	v_add_f32_e32 v80, v80, v68
	v_add_f32_e32 v81, v81, v69
	v_add_f32_e32 v82, v82, v70
	v_add_f32_e32 v83, v83, v71
	v_add_f32_e32 v84, v84, v72
	v_add_f32_e32 v85, v85, v73
	v_add_f32_e32 v86, v86, v74
	v_add_f32_e32 v87, v87, v75
	ds_bpermute_b32 v64, v14, v76
	ds_bpermute_b32 v65, v14, v77
	ds_bpermute_b32 v66, v14, v78
	ds_bpermute_b32 v67, v14, v79
	ds_bpermute_b32 v68, v14, v80
	ds_bpermute_b32 v69, v14, v81
	ds_bpermute_b32 v70, v14, v82
	ds_bpermute_b32 v71, v14, v83
	ds_bpermute_b32 v72, v14, v84
	ds_bpermute_b32 v73, v14, v85
	ds_bpermute_b32 v74, v14, v86
	ds_bpermute_b32 v75, v14, v87
	s_waitcnt lgkmcnt(0)
	v_add_f32_e32 v76, v76, v64
	v_add_f32_e32 v77, v77, v65
	v_add_f32_e32 v78, v78, v66
	v_add_f32_e32 v79, v79, v67
	v_add_f32_e32 v80, v80, v68
	v_add_f32_e32 v81, v81, v69
	v_add_f32_e32 v82, v82, v70
	v_add_f32_e32 v83, v83, v71
	v_add_f32_e32 v84, v84, v72
	v_add_f32_e32 v85, v85, v73
	v_add_f32_e32 v86, v86, v74
	v_add_f32_e32 v87, v87, v75
	ds_bpermute_b32 v64, v15, v76
	ds_bpermute_b32 v65, v15, v77
	ds_bpermute_b32 v66, v15, v78
	ds_bpermute_b32 v67, v15, v79
	ds_bpermute_b32 v68, v15, v80
	ds_bpermute_b32 v69, v15, v81
	ds_bpermute_b32 v70, v15, v82
	ds_bpermute_b32 v71, v15, v83
	ds_bpermute_b32 v72, v15, v84
	ds_bpermute_b32 v73, v15, v85
	ds_bpermute_b32 v74, v15, v86
	ds_bpermute_b32 v75, v15, v87
	s_waitcnt lgkmcnt(0)
	v_add_f32_e32 v76, v76, v64
	v_add_f32_e32 v77, v77, v65
	v_add_f32_e32 v78, v78, v66
	v_add_f32_e32 v79, v79, v67
	v_add_f32_e32 v80, v80, v68
	v_add_f32_e32 v81, v81, v69
	v_add_f32_e32 v82, v82, v70
	v_add_f32_e32 v83, v83, v71
	v_add_f32_e32 v84, v84, v72
	v_add_f32_e32 v85, v85, v73
	v_add_f32_e32 v86, v86, v74
	v_add_f32_e32 v87, v87, v75
	ds_bpermute_b32 v64, v16, v76
	ds_bpermute_b32 v65, v16, v77
	ds_bpermute_b32 v66, v16, v78
	ds_bpermute_b32 v67, v16, v79
	ds_bpermute_b32 v68, v16, v80
	ds_bpermute_b32 v69, v16, v81
	ds_bpermute_b32 v70, v16, v82
	ds_bpermute_b32 v71, v16, v83
	ds_bpermute_b32 v72, v16, v84
	ds_bpermute_b32 v73, v16, v85
	ds_bpermute_b32 v74, v16, v86
	ds_bpermute_b32 v75, v16, v87
	s_waitcnt lgkmcnt(0)
; DI float bf2f(u16 h) { return __uint_as_float(((unsigned)h) << 16); }
; DI void nsa_prep_item(const Params& P, int l, int it) {
;     ...
;     for (int g = 0; g < 6; ++g) {
;       const int col = (g < 4) ? (P_Q + g * 64) : (g == 4 ? P_KV + 128 : P_KV + 256);
;       const float wg = (g < 4) ? P.in[4][l * 64 + lane] : P.in[5][(l * 3 + (g - 3)) * 64 + lane];
;       u16* ptr = PROJ + t * PW + col + lane;
;       float v = bf2f(*ptr);
;       float ss = wave_sum(v * v);
;       float y = v * rsqrtf(ss * (1.f / 64.f) + EPS) * wg;
;       float pr = __shfl_xor(y, 8);
;       float rot = (lane < 8) ? (y * cs - pr * sn) : ((lane < 16) ? (y * cs + pr * sn) : y);
;       if (g < 4) { *ptr = f2bf(y); QR[t * 256 + g * 64 + lane] = f2bf(rot); }
;       else *ptr = f2bf(rot);
;     }
	v_add_f32_e32 v76, v76, v64
	v_add_f32_e32 v77, v77, v65
	v_add_f32_e32 v78, v78, v66
	v_add_f32_e32 v79, v79, v67
	v_add_f32_e32 v80, v80, v68
	v_add_f32_e32 v81, v81, v69
	v_add_f32_e32 v82, v82, v70
	v_add_f32_e32 v83, v83, v71
	v_add_f32_e32 v84, v84, v72
	v_add_f32_e32 v85, v85, v73
	v_add_f32_e32 v86, v86, v74
	v_add_f32_e32 v87, v87, v75
	v_fmamk_f32 v76, v76, 0x3c800000, v164
	v_fmamk_f32 v77, v77, 0x3c800000, v164
	v_fmamk_f32 v78, v78, 0x3c800000, v164
	v_fmamk_f32 v79, v79, 0x3c800000, v164
	v_fmamk_f32 v80, v80, 0x3c800000, v164
	v_fmamk_f32 v81, v81, 0x3c800000, v164
	v_fmamk_f32 v82, v82, 0x3c800000, v164
	v_fmamk_f32 v83, v83, 0x3c800000, v164
	v_fmamk_f32 v84, v84, 0x3c800000, v164
	v_fmamk_f32 v85, v85, 0x3c800000, v164
	v_fmamk_f32 v86, v86, 0x3c800000, v164
	v_fmamk_f32 v87, v87, 0x3c800000, v164
	v_rsq_f32_e32 v76, v76
	v_rsq_f32_e32 v77, v77
	v_rsq_f32_e32 v78, v78
	v_rsq_f32_e32 v79, v79
	v_rsq_f32_e32 v80, v80
	v_rsq_f32_e32 v81, v81
	v_rsq_f32_e32 v82, v82
	v_rsq_f32_e32 v83, v83
	v_rsq_f32_e32 v84, v84
	v_rsq_f32_e32 v85, v85
	v_rsq_f32_e32 v86, v86
	v_rsq_f32_e32 v87, v87
	v_mul_f32_e32 v40, v76, v40
	v_mul_f32_e32 v41, v77, v41
	v_mul_f32_e32 v42, v78, v42
	v_mul_f32_e32 v43, v79, v43
	v_mul_f32_e32 v44, v80, v44
	v_mul_f32_e32 v45, v81, v45
	v_mul_f32_e32 v46, v82, v46
	v_mul_f32_e32 v47, v83, v47
	v_mul_f32_e32 v48, v84, v48
	v_mul_f32_e32 v49, v85, v49
	v_mul_f32_e32 v50, v86, v50
	v_mul_f32_e32 v51, v87, v51
	v_mul_f32_e32 v40, v8, v40
	v_mul_f32_e32 v41, v8, v41
	v_mul_f32_e32 v42, v8, v42
	v_mul_f32_e32 v43, v8, v43
	v_mul_f32_e32 v44, v9, v44
	v_mul_f32_e32 v45, v10, v45
	v_mul_f32_e32 v46, v8, v46
	v_mul_f32_e32 v47, v8, v47
	v_mul_f32_e32 v48, v8, v48
	v_mul_f32_e32 v49, v8, v49
	v_mul_f32_e32 v50, v9, v50
	v_mul_f32_e32 v51, v10, v51
	ds_bpermute_b32 v64, v14, v40
	ds_bpermute_b32 v65, v14, v41
	ds_bpermute_b32 v66, v14, v42
	ds_bpermute_b32 v67, v14, v43
	ds_bpermute_b32 v68, v14, v44
	ds_bpermute_b32 v69, v14, v45
	ds_bpermute_b32 v70, v14, v46
	ds_bpermute_b32 v71, v14, v47
	ds_bpermute_b32 v72, v14, v48
	ds_bpermute_b32 v73, v14, v49
	ds_bpermute_b32 v74, v14, v50
	ds_bpermute_b32 v75, v14, v51
	v_mul_f32_e32 v88, v32, v40
	v_mul_f32_e32 v89, v32, v41
	v_mul_f32_e32 v90, v32, v42
	v_mul_f32_e32 v91, v32, v43
	v_mul_f32_e32 v92, v32, v44
	v_mul_f32_e32 v93, v32, v45
	v_mul_f32_e32 v94, v33, v46
	v_mul_f32_e32 v95, v33, v47
	v_mul_f32_e32 v96, v33, v48
	v_mul_f32_e32 v97, v33, v49
	v_mul_f32_e32 v98, v33, v50
	v_mul_f32_e32 v99, v33, v51
	v_cvt_pk_bf16_f32 v76, v40, v40
	v_cvt_pk_bf16_f32 v77, v41, v41
	v_cvt_pk_bf16_f32 v78, v42, v42
	v_cvt_pk_bf16_f32 v79, v43, v43
	v_cvt_pk_bf16_f32 v82, v46, v46
	v_cvt_pk_bf16_f32 v83, v47, v47
	v_cvt_pk_bf16_f32 v84, v48, v48
	v_cvt_pk_bf16_f32 v85, v49, v49
	global_store_short v[6:7], v76, off offset:-768
	global_store_short v[6:7], v77, off offset:-640
	global_store_short v[6:7], v78, off offset:-512
	global_store_short v[6:7], v79, off offset:-384
	global_store_short v[26:27], v82, off offset:-768
	global_store_short v[26:27], v83, off offset:-640
	global_store_short v[26:27], v84, off offset:-512
	global_store_short v[26:27], v85, off offset:-384
	s_waitcnt lgkmcnt(0)
	v_fma_f32 v100, -v36, v64, v88
	v_fma_f32 v101, -v36, v65, v89
	v_fma_f32 v102, -v36, v66, v90
	v_fma_f32 v103, -v36, v67, v91
	v_fma_f32 v104, -v36, v68, v92
	v_fma_f32 v105, -v36, v69, v93
	v_fma_f32 v106, -v37, v70, v94
	v_fma_f32 v107, -v37, v71, v95
	v_fma_f32 v108, -v37, v72, v96
	v_fma_f32 v109, -v37, v73, v97
	v_fma_f32 v110, -v37, v74, v98
	v_fma_f32 v111, -v37, v75, v99
	v_fmac_f32_e32 v88, v36, v64
	v_fmac_f32_e32 v89, v36, v65
	v_fmac_f32_e32 v90, v36, v66
	v_fmac_f32_e32 v91, v36, v67
	v_fmac_f32_e32 v92, v36, v68
	v_fmac_f32_e32 v93, v36, v69
	v_fmac_f32_e32 v94, v37, v70
	v_fmac_f32_e32 v95, v37, v71
	v_fmac_f32_e32 v96, v37, v72
	v_fmac_f32_e32 v97, v37, v73
	v_fmac_f32_e32 v98, v37, v74
	v_fmac_f32_e32 v99, v37, v75
	v_cndmask_b32_e64 v40, v40, v88, s[0:1]
	v_cndmask_b32_e64 v41, v41, v89, s[0:1]
	v_cndmask_b32_e64 v42, v42, v90, s[0:1]
	v_cndmask_b32_e64 v43, v43, v91, s[0:1]
	v_cndmask_b32_e64 v44, v44, v92, s[0:1]
	v_cndmask_b32_e64 v45, v45, v93, s[0:1]
	v_cndmask_b32_e64 v46, v46, v94, s[0:1]
	v_cndmask_b32_e64 v47, v47, v95, s[0:1]
	v_cndmask_b32_e64 v48, v48, v96, s[0:1]
	v_cndmask_b32_e64 v49, v49, v97, s[0:1]
	v_cndmask_b32_e64 v50, v50, v98, s[0:1]
	v_cndmask_b32_e64 v51, v51, v99, s[0:1]
	v_cndmask_b32_e32 v40, v40, v100, vcc
	v_cndmask_b32_e32 v41, v41, v101, vcc
	v_cndmask_b32_e32 v42, v42, v102, vcc
	v_cndmask_b32_e32 v43, v43, v103, vcc
	v_cndmask_b32_e32 v44, v44, v104, vcc
	v_cndmask_b32_e32 v45, v45, v105, vcc
	v_cndmask_b32_e32 v46, v46, v106, vcc
	v_cndmask_b32_e32 v47, v47, v107, vcc
	v_cndmask_b32_e32 v48, v48, v108, vcc
	v_cndmask_b32_e32 v49, v49, v109, vcc
	v_cndmask_b32_e32 v50, v50, v110, vcc
	v_cndmask_b32_e32 v51, v51, v111, vcc
	v_cvt_pk_bf16_f32 v40, v40, v40
	v_cvt_pk_bf16_f32 v41, v41, v41
	v_cvt_pk_bf16_f32 v42, v42, v42
	v_cvt_pk_bf16_f32 v43, v43, v43
	v_cvt_pk_bf16_f32 v44, v44, v44
	v_cvt_pk_bf16_f32 v45, v45, v45
	v_cvt_pk_bf16_f32 v46, v46, v46
	v_cvt_pk_bf16_f32 v47, v47, v47
	v_cvt_pk_bf16_f32 v48, v48, v48
	v_cvt_pk_bf16_f32 v49, v49, v49
	v_cvt_pk_bf16_f32 v50, v50, v50
	v_cvt_pk_bf16_f32 v51, v51, v51
	global_store_short v[4:5], v40, off offset:-256
	global_store_short v[4:5], v41, off offset:-128
	global_store_short v[4:5], v42, off offset:0
	global_store_short v[4:5], v43, off offset:128
	global_store_short v[6:7], v44, off
	global_store_short v[6:7], v45, off offset:256
	global_store_short v[4:5], v46, off offset:256
	global_store_short v[4:5], v47, off offset:384
	global_store_short v[4:5], v48, off offset:512
	global_store_short v[4:5], v49, off offset:640
	global_store_short v[26:27], v50, off
	global_store_short v[26:27], v51, off offset:256
	v_lshlrev_b32_e32 v52, 16, v52
	v_lshlrev_b32_e32 v53, 16, v53
	v_lshlrev_b32_e32 v54, 16, v54
	v_lshlrev_b32_e32 v55, 16, v55
	v_lshlrev_b32_e32 v56, 16, v56
	v_lshlrev_b32_e32 v57, 16, v57
	v_lshlrev_b32_e32 v58, 16, v58
	v_lshlrev_b32_e32 v59, 16, v59
	v_lshlrev_b32_e32 v60, 16, v60
	v_lshlrev_b32_e32 v61, 16, v61
	v_lshlrev_b32_e32 v62, 16, v62
	v_lshlrev_b32_e32 v63, 16, v63
	v_mul_f32_e32 v64, v52, v52
	v_mul_f32_e32 v65, v53, v53
	v_mul_f32_e32 v66, v54, v54
	v_mul_f32_e32 v67, v55, v55
	v_mul_f32_e32 v68, v56, v56
	v_mul_f32_e32 v69, v57, v57
	v_mul_f32_e32 v70, v58, v58
	v_mul_f32_e32 v71, v59, v59
	v_mul_f32_e32 v72, v60, v60
	v_mul_f32_e32 v73, v61, v61
	v_mul_f32_e32 v74, v62, v62
	v_mul_f32_e32 v75, v63, v63
	ds_bpermute_b32 v76, v11, v64
	ds_bpermute_b32 v77, v11, v65
	ds_bpermute_b32 v78, v11, v66
	ds_bpermute_b32 v79, v11, v67
	ds_bpermute_b32 v80, v11, v68
	ds_bpermute_b32 v81, v11, v69
	ds_bpermute_b32 v82, v11, v70
	ds_bpermute_b32 v83, v11, v71
	ds_bpermute_b32 v84, v11, v72
	ds_bpermute_b32 v85, v11, v73
	ds_bpermute_b32 v86, v11, v74
	ds_bpermute_b32 v87, v11, v75
	s_waitcnt lgkmcnt(0)
; DI float bf2f(u16 h) { return __uint_as_float(((unsigned)h) << 16); }
; DI void nsa_prep_item(const Params& P, int l, int it) {
;     ...
;     for (int g = 0; g < 6; ++g) {
;       const int col = (g < 4) ? (P_Q + g * 64) : (g == 4 ? P_KV + 128 : P_KV + 256);
;       const float wg = (g < 4) ? P.in[4][l * 64 + lane] : P.in[5][(l * 3 + (g - 3)) * 64 + lane];
;       u16* ptr = PROJ + t * PW + col + lane;
;       float v = bf2f(*ptr);
;       float ss = wave_sum(v * v);
;       float y = v * rsqrtf(ss * (1.f / 64.f) + EPS) * wg;
	v_fmac_f32_e32 v76, v52, v52
	v_fmac_f32_e32 v77, v53, v53
	v_fmac_f32_e32 v78, v54, v54
	v_fmac_f32_e32 v79, v55, v55
	v_fmac_f32_e32 v80, v56, v56
	v_fmac_f32_e32 v81, v57, v57
	v_fmac_f32_e32 v82, v58, v58
	v_fmac_f32_e32 v83, v59, v59
	v_fmac_f32_e32 v84, v60, v60
	v_fmac_f32_e32 v85, v61, v61
	v_fmac_f32_e32 v86, v62, v62
	v_fmac_f32_e32 v87, v63, v63
	ds_bpermute_b32 v64, v12, v76
	ds_bpermute_b32 v65, v12, v77
	ds_bpermute_b32 v66, v12, v78
	ds_bpermute_b32 v67, v12, v79
	ds_bpermute_b32 v68, v12, v80
	ds_bpermute_b32 v69, v12, v81
	ds_bpermute_b32 v70, v12, v82
	ds_bpermute_b32 v71, v12, v83
	ds_bpermute_b32 v72, v12, v84
	ds_bpermute_b32 v73, v12, v85
	ds_bpermute_b32 v74, v12, v86
	ds_bpermute_b32 v75, v12, v87
	s_waitcnt lgkmcnt(0)
	v_add_f32_e32 v76, v76, v64
	v_add_f32_e32 v77, v77, v65
	v_add_f32_e32 v78, v78, v66
	v_add_f32_e32 v79, v79, v67
	v_add_f32_e32 v80, v80, v68
	v_add_f32_e32 v81, v81, v69
	v_add_f32_e32 v82, v82, v70
	v_add_f32_e32 v83, v83, v71
	v_add_f32_e32 v84, v84, v72
	v_add_f32_e32 v85, v85, v73
	v_add_f32_e32 v86, v86, v74
	v_add_f32_e32 v87, v87, v75
	ds_bpermute_b32 v64, v13, v76
	ds_bpermute_b32 v65, v13, v77
	ds_bpermute_b32 v66, v13, v78
	ds_bpermute_b32 v67, v13, v79
	ds_bpermute_b32 v68, v13, v80
	ds_bpermute_b32 v69, v13, v81
	ds_bpermute_b32 v70, v13, v82
	ds_bpermute_b32 v71, v13, v83
	ds_bpermute_b32 v72, v13, v84
	ds_bpermute_b32 v73, v13, v85
	ds_bpermute_b32 v74, v13, v86
	ds_bpermute_b32 v75, v13, v87
	s_waitcnt lgkmcnt(0)
	v_add_f32_e32 v76, v76, v64
	v_add_f32_e32 v77, v77, v65
	v_add_f32_e32 v78, v78, v66
	v_add_f32_e32 v79, v79, v67
	v_add_f32_e32 v80, v80, v68
	v_add_f32_e32 v81, v81, v69
	v_add_f32_e32 v82, v82, v70
	v_add_f32_e32 v83, v83, v71
	v_add_f32_e32 v84, v84, v72
	v_add_f32_e32 v85, v85, v73
	v_add_f32_e32 v86, v86, v74
	v_add_f32_e32 v87, v87, v75
	ds_bpermute_b32 v64, v14, v76
	ds_bpermute_b32 v65, v14, v77
	ds_bpermute_b32 v66, v14, v78
	ds_bpermute_b32 v67, v14, v79
	ds_bpermute_b32 v68, v14, v80
	ds_bpermute_b32 v69, v14, v81
	ds_bpermute_b32 v70, v14, v82
	ds_bpermute_b32 v71, v14, v83
	ds_bpermute_b32 v72, v14, v84
	ds_bpermute_b32 v73, v14, v85
	ds_bpermute_b32 v74, v14, v86
	ds_bpermute_b32 v75, v14, v87
	s_waitcnt lgkmcnt(0)
	v_add_f32_e32 v76, v76, v64
	v_add_f32_e32 v77, v77, v65
	v_add_f32_e32 v78, v78, v66
	v_add_f32_e32 v79, v79, v67
	v_add_f32_e32 v80, v80, v68
	v_add_f32_e32 v81, v81, v69
	v_add_f32_e32 v82, v82, v70
	v_add_f32_e32 v83, v83, v71
	v_add_f32_e32 v84, v84, v72
	v_add_f32_e32 v85, v85, v73
	v_add_f32_e32 v86, v86, v74
	v_add_f32_e32 v87, v87, v75
	ds_bpermute_b32 v64, v15, v76
	ds_bpermute_b32 v65, v15, v77
	ds_bpermute_b32 v66, v15, v78
	ds_bpermute_b32 v67, v15, v79
	ds_bpermute_b32 v68, v15, v80
	ds_bpermute_b32 v69, v15, v81
	ds_bpermute_b32 v70, v15, v82
	ds_bpermute_b32 v71, v15, v83
	ds_bpermute_b32 v72, v15, v84
	ds_bpermute_b32 v73, v15, v85
	ds_bpermute_b32 v74, v15, v86
	ds_bpermute_b32 v75, v15, v87
	s_waitcnt lgkmcnt(0)
	v_add_f32_e32 v76, v76, v64
	v_add_f32_e32 v77, v77, v65
	v_add_f32_e32 v78, v78, v66
	v_add_f32_e32 v79, v79, v67
	v_add_f32_e32 v80, v80, v68
	v_add_f32_e32 v81, v81, v69
	v_add_f32_e32 v82, v82, v70
	v_add_f32_e32 v83, v83, v71
	v_add_f32_e32 v84, v84, v72
	v_add_f32_e32 v85, v85, v73
	v_add_f32_e32 v86, v86, v74
	v_add_f32_e32 v87, v87, v75
	ds_bpermute_b32 v64, v16, v76
	ds_bpermute_b32 v65, v16, v77
	ds_bpermute_b32 v66, v16, v78
	ds_bpermute_b32 v67, v16, v79
	ds_bpermute_b32 v68, v16, v80
	ds_bpermute_b32 v69, v16, v81
	ds_bpermute_b32 v70, v16, v82
	ds_bpermute_b32 v71, v16, v83
	ds_bpermute_b32 v72, v16, v84
	ds_bpermute_b32 v73, v16, v85
	ds_bpermute_b32 v74, v16, v86
	ds_bpermute_b32 v75, v16, v87
	s_waitcnt lgkmcnt(0)
; DI float bf2f(u16 h) { return __uint_as_float(((unsigned)h) << 16); }
; DI void nsa_prep_item(const Params& P, int l, int it) {
;     ...
;     for (int g = 0; g < 6; ++g) {
;       const int col = (g < 4) ? (P_Q + g * 64) : (g == 4 ? P_KV + 128 : P_KV + 256);
;       const float wg = (g < 4) ? P.in[4][l * 64 + lane] : P.in[5][(l * 3 + (g - 3)) * 64 + lane];
;       u16* ptr = PROJ + t * PW + col + lane;
;       float v = bf2f(*ptr);
;       float ss = wave_sum(v * v);
;       float y = v * rsqrtf(ss * (1.f / 64.f) + EPS) * wg;
;       float pr = __shfl_xor(y, 8);
;       float rot = (lane < 8) ? (y * cs - pr * sn) : ((lane < 16) ? (y * cs + pr * sn) : y);
;       if (g < 4) { *ptr = f2bf(y); QR[t * 256 + g * 64 + lane] = f2bf(rot); }
;       else *ptr = f2bf(rot);
;     }
	v_add_f32_e32 v76, v76, v64
	v_add_f32_e32 v77, v77, v65
	v_add_f32_e32 v78, v78, v66
	v_add_f32_e32 v79, v79, v67
	v_add_f32_e32 v80, v80, v68
	v_add_f32_e32 v81, v81, v69
	v_add_f32_e32 v82, v82, v70
	v_add_f32_e32 v83, v83, v71
	v_add_f32_e32 v84, v84, v72
	v_add_f32_e32 v85, v85, v73
	v_add_f32_e32 v86, v86, v74
	v_add_f32_e32 v87, v87, v75
	v_fmamk_f32 v76, v76, 0x3c800000, v164
	v_fmamk_f32 v77, v77, 0x3c800000, v164
	v_fmamk_f32 v78, v78, 0x3c800000, v164
	v_fmamk_f32 v79, v79, 0x3c800000, v164
	v_fmamk_f32 v80, v80, 0x3c800000, v164
	v_fmamk_f32 v81, v81, 0x3c800000, v164
	v_fmamk_f32 v82, v82, 0x3c800000, v164
	v_fmamk_f32 v83, v83, 0x3c800000, v164
	v_fmamk_f32 v84, v84, 0x3c800000, v164
	v_fmamk_f32 v85, v85, 0x3c800000, v164
	v_fmamk_f32 v86, v86, 0x3c800000, v164
	v_fmamk_f32 v87, v87, 0x3c800000, v164
	v_rsq_f32_e32 v76, v76
	v_rsq_f32_e32 v77, v77
	v_rsq_f32_e32 v78, v78
	v_rsq_f32_e32 v79, v79
	v_rsq_f32_e32 v80, v80
	v_rsq_f32_e32 v81, v81
	v_rsq_f32_e32 v82, v82
	v_rsq_f32_e32 v83, v83
	v_rsq_f32_e32 v84, v84
	v_rsq_f32_e32 v85, v85
	v_rsq_f32_e32 v86, v86
	v_rsq_f32_e32 v87, v87
	v_mul_f32_e32 v52, v76, v52
	v_mul_f32_e32 v53, v77, v53
	v_mul_f32_e32 v54, v78, v54
	v_mul_f32_e32 v55, v79, v55
	v_mul_f32_e32 v56, v80, v56
	v_mul_f32_e32 v57, v81, v57
	v_mul_f32_e32 v58, v82, v58
	v_mul_f32_e32 v59, v83, v59
	v_mul_f32_e32 v60, v84, v60
	v_mul_f32_e32 v61, v85, v61
	v_mul_f32_e32 v62, v86, v62
	v_mul_f32_e32 v63, v87, v63
	v_mul_f32_e32 v52, v8, v52
	v_mul_f32_e32 v53, v8, v53
	v_mul_f32_e32 v54, v8, v54
	v_mul_f32_e32 v55, v8, v55
	v_mul_f32_e32 v56, v9, v56
	v_mul_f32_e32 v57, v10, v57
	v_mul_f32_e32 v58, v8, v58
	v_mul_f32_e32 v59, v8, v59
	v_mul_f32_e32 v60, v8, v60
	v_mul_f32_e32 v61, v8, v61
	v_mul_f32_e32 v62, v9, v62
	v_mul_f32_e32 v63, v10, v63
	ds_bpermute_b32 v64, v14, v52
	ds_bpermute_b32 v65, v14, v53
	ds_bpermute_b32 v66, v14, v54
	ds_bpermute_b32 v67, v14, v55
	ds_bpermute_b32 v68, v14, v56
	ds_bpermute_b32 v69, v14, v57
	ds_bpermute_b32 v70, v14, v58
	ds_bpermute_b32 v71, v14, v59
	ds_bpermute_b32 v72, v14, v60
	ds_bpermute_b32 v73, v14, v61
	ds_bpermute_b32 v74, v14, v62
	ds_bpermute_b32 v75, v14, v63
	v_mul_f32_e32 v88, v34, v52
	v_mul_f32_e32 v89, v34, v53
	v_mul_f32_e32 v90, v34, v54
	v_mul_f32_e32 v91, v34, v55
	v_mul_f32_e32 v92, v34, v56
	v_mul_f32_e32 v93, v34, v57
	v_mul_f32_e32 v94, v35, v58
	v_mul_f32_e32 v95, v35, v59
	v_mul_f32_e32 v96, v35, v60
	v_mul_f32_e32 v97, v35, v61
	v_mul_f32_e32 v98, v35, v62
	v_mul_f32_e32 v99, v35, v63
	v_cvt_pk_bf16_f32 v76, v52, v52
	v_cvt_pk_bf16_f32 v77, v53, v53
	v_cvt_pk_bf16_f32 v78, v54, v54
	v_cvt_pk_bf16_f32 v79, v55, v55
	v_cvt_pk_bf16_f32 v82, v58, v58
	v_cvt_pk_bf16_f32 v83, v59, v59
	v_cvt_pk_bf16_f32 v84, v60, v60
	v_cvt_pk_bf16_f32 v85, v61, v61
	global_store_short v[28:29], v76, off offset:-768
	global_store_short v[28:29], v77, off offset:-640
	global_store_short v[28:29], v78, off offset:-512
	global_store_short v[28:29], v79, off offset:-384
	global_store_short v[30:31], v82, off offset:-768
	global_store_short v[30:31], v83, off offset:-640
	global_store_short v[30:31], v84, off offset:-512
	global_store_short v[30:31], v85, off offset:-384
	s_waitcnt lgkmcnt(0)
	v_fma_f32 v100, -v38, v64, v88
	v_fma_f32 v101, -v38, v65, v89
	v_fma_f32 v102, -v38, v66, v90
	v_fma_f32 v103, -v38, v67, v91
	v_fma_f32 v104, -v38, v68, v92
	v_fma_f32 v105, -v38, v69, v93
	v_fma_f32 v106, -v39, v70, v94
	v_fma_f32 v107, -v39, v71, v95
	v_fma_f32 v108, -v39, v72, v96
	v_fma_f32 v109, -v39, v73, v97
	v_fma_f32 v110, -v39, v74, v98
	v_fma_f32 v111, -v39, v75, v99
	v_fmac_f32_e32 v88, v38, v64
	v_fmac_f32_e32 v89, v38, v65
	v_fmac_f32_e32 v90, v38, v66
	v_fmac_f32_e32 v91, v38, v67
	v_fmac_f32_e32 v92, v38, v68
	v_fmac_f32_e32 v93, v38, v69
	v_fmac_f32_e32 v94, v39, v70
	v_fmac_f32_e32 v95, v39, v71
	v_fmac_f32_e32 v96, v39, v72
	v_fmac_f32_e32 v97, v39, v73
	v_fmac_f32_e32 v98, v39, v74
	v_fmac_f32_e32 v99, v39, v75
	v_cndmask_b32_e64 v52, v52, v88, s[0:1]
	v_cndmask_b32_e64 v53, v53, v89, s[0:1]
	v_cndmask_b32_e64 v54, v54, v90, s[0:1]
	v_cndmask_b32_e64 v55, v55, v91, s[0:1]
	v_cndmask_b32_e64 v56, v56, v92, s[0:1]
	v_cndmask_b32_e64 v57, v57, v93, s[0:1]
	v_cndmask_b32_e64 v58, v58, v94, s[0:1]
	v_cndmask_b32_e64 v59, v59, v95, s[0:1]
	v_cndmask_b32_e64 v60, v60, v96, s[0:1]
	v_cndmask_b32_e64 v61, v61, v97, s[0:1]
	v_cndmask_b32_e64 v62, v62, v98, s[0:1]
	v_cndmask_b32_e64 v63, v63, v99, s[0:1]
	v_cndmask_b32_e32 v52, v52, v100, vcc
	v_cndmask_b32_e32 v53, v53, v101, vcc
	v_cndmask_b32_e32 v54, v54, v102, vcc
	v_cndmask_b32_e32 v55, v55, v103, vcc
	v_cndmask_b32_e32 v56, v56, v104, vcc
	v_cndmask_b32_e32 v57, v57, v105, vcc
	v_cndmask_b32_e32 v58, v58, v106, vcc
	v_cndmask_b32_e32 v59, v59, v107, vcc
	v_cndmask_b32_e32 v60, v60, v108, vcc
	v_cndmask_b32_e32 v61, v61, v109, vcc
	v_cndmask_b32_e32 v62, v62, v110, vcc
	v_cndmask_b32_e32 v63, v63, v111, vcc
	v_cvt_pk_bf16_f32 v52, v52, v52
	v_cvt_pk_bf16_f32 v53, v53, v53
	v_cvt_pk_bf16_f32 v54, v54, v54
	v_cvt_pk_bf16_f32 v55, v55, v55
	v_cvt_pk_bf16_f32 v56, v56, v56
	v_cvt_pk_bf16_f32 v57, v57, v57
	v_cvt_pk_bf16_f32 v58, v58, v58
	v_cvt_pk_bf16_f32 v59, v59, v59
	v_cvt_pk_bf16_f32 v60, v60, v60
	v_cvt_pk_bf16_f32 v61, v61, v61
	v_cvt_pk_bf16_f32 v62, v62, v62
	v_cvt_pk_bf16_f32 v63, v63, v63
	global_store_short v[4:5], v52, off offset:768
	global_store_short v[4:5], v53, off offset:896
	global_store_short v[4:5], v54, off offset:1024
	global_store_short v[4:5], v55, off offset:1152
	global_store_short v[28:29], v56, off
	global_store_short v[28:29], v57, off offset:256
	global_store_short v[4:5], v58, off offset:1280
	global_store_short v[4:5], v59, off offset:1408
	global_store_short v[4:5], v60, off offset:1536
	global_store_short v[4:5], v61, off offset:1664
	global_store_short v[30:31], v62, off
	global_store_short v[30:31], v63, off offset:256
	s_mov_b64 s[0:1], 0
